# previous + K-fragment address via v_mad_u32_u24 instead of v_mad_u64_u32 in attention step loop
# speedup vs baseline: 1.0090x; 1.0022x over previous
.LBB0_790:
	s_waitcnt lgkmcnt(3)
	v_mfma_f32_16x16x32_bf16 v[152:155], v[144:147], v[72:75], v[228:231]
	s_waitcnt lgkmcnt(2)
	v_mfma_f32_16x16x32_bf16 v[192:195], v[148:151], v[76:79], v[152:155]
	v_mfma_f32_16x16x32_bf16 v[152:155], v[144:147], v[84:87], v[232:235]
	v_mfma_f32_16x16x32_bf16 v[180:183], v[148:151], v[88:91], v[152:155]
	s_mov_b32 s6, s53
	s_add_i32 s53, s53, 1
	s_cmp_ge_u32 s53, s52
	v_mfma_f32_16x16x32_bf16 v[152:155], v[144:147], v[100:103], v[248:251]
	s_cselect_b64 s[34:35], -1, 0
	s_cmp_lt_u32 s53, s52
	s_cselect_b32 s6, s53, s6
	v_mfma_f32_16x16x32_bf16 v[144:147], v[144:147], v[108:111], v[220:223]
	v_lshl_or_b32 v37, s6, 5, v201
	v_mad_u32_u24 v38, v37, s3, v32
	v_mfma_f32_16x16x32_bf16 v[156:159], v[148:151], v[104:107], v[152:155]
	v_mfma_f32_16x16x32_bf16 v[152:155], v[148:151], v[112:115], v[144:147]
	s_waitcnt lgkmcnt(1)
	v_mfma_f32_16x16x32_bf16 v[144:147], v[140:143], v[72:75], v[228:231]
	s_waitcnt lgkmcnt(0)
	v_mfma_f32_16x16x32_bf16 v[196:199], v[136:139], v[76:79], v[144:147]
	s_nop 0
	v_mfma_f32_16x16x32_bf16 v[144:147], v[140:143], v[84:87], v[232:235]
	v_mfma_f32_16x16x32_bf16 v[188:191], v[136:139], v[88:91], v[144:147]
	v_mfma_f32_16x16x32_bf16 v[144:147], v[140:143], v[100:103], v[248:251]
	v_mfma_f32_16x16x32_bf16 v[140:143], v[140:143], v[108:111], v[220:223]
	v_mfma_f32_16x16x32_bf16 v[184:187], v[136:139], v[104:107], v[144:147]
	s_nop 5
	ds_read_b128 v[144:147], v38
	ds_read_b128 v[148:151], v38 offset:64
	v_mfma_f32_16x16x32_bf16 v[172:175], v[136:139], v[112:115], v[140:143]
	s_nop 2
	ds_read_b128 v[140:143], v38 offset:2304
	ds_read_b128 v[136:139], v38 offset:2368
	ds_read_b64_tr_b16 v[168:169], v35
	ds_read_b64_tr_b16 v[170:171], v35 offset:2560
	ds_read_b64_tr_b16 v[160:161], v35 offset:32
	ds_read_b64_tr_b16 v[162:163], v35 offset:2592
	ds_read_b64_tr_b16 v[176:177], v35 offset:64
	ds_read_b64_tr_b16 v[178:179], v35 offset:2624
	ds_read_b64_tr_b16 v[164:165], v35 offset:96
	ds_read_b64_tr_b16 v[166:167], v35 offset:2656
	s_andn2_b64 vcc, exec, s[86:87]
	s_cbranch_vccnz .LBB0_792
	s_mul_i32 s30, s54, 0xffffffd0
	v_mov_b32_e32 v38, s4
	v_cmp_lt_i32_e64 s[30:31], s30, v34
	s_mul_i32 s10, s54, 3
	s_mul_i32 s16, s54, -15
	v_cndmask_b32_e64 v152, v152, v38, s[30:31]
	s_mul_i32 s30, s54, 0xffffffd1
	v_cmp_ge_i32_e64 s[30:31], s30, v34
	s_mul_i32 s18, s54, -14
	s_mul_i32 s20, s54, -13
	v_cndmask_b32_e64 v153, v241, v153, s[30:31]
	s_mul_i32 s30, s54, 0xffffffd2
	v_cmp_ge_i32_e64 s[30:31], s30, v34
	s_mul_i32 s24, s54, 0xffffffe1
	s_mul_i32 s26, s54, 0xffffffe2
	v_cndmask_b32_e64 v154, v241, v154, s[30:31]
	s_mul_i32 s30, s54, 0xffffffd3
	v_cmp_ge_i32_e64 s[30:31], s30, v34
	s_mul_i32 s28, s54, 0xffffffe3
	v_cmp_lt_i32_e32 vcc, 0, v34
	v_cndmask_b32_e64 v155, v241, v155, s[30:31]
	v_cmp_lt_i32_e64 s[30:31], s84, v34
	v_cmp_lt_i32_e64 s[6:7], s54, v34
	v_cmp_lt_i32_e64 s[8:9], s55, v34
	v_cndmask_b32_e64 v196, v196, v38, s[30:31]
	s_mul_i32 s30, s54, 17
	v_cmp_ge_i32_e64 s[30:31], s30, v34
	v_cmp_lt_i32_e64 s[10:11], s10, v34
	v_cmp_lt_i32_e64 s[12:13], s85, v34
	v_cndmask_b32_e64 v197, v241, v197, s[30:31]
	s_mul_i32 s30, s54, 18
	v_cmp_ge_i32_e64 s[30:31], s30, v34
	v_cmp_lt_i32_e64 s[16:17], s16, v34
	v_cmp_lt_i32_e64 s[18:19], s18, v34
	v_cndmask_b32_e64 v198, v241, v198, s[30:31]
	s_mul_i32 s30, s54, 19
	v_cmp_lt_i32_e64 s[20:21], s20, v34
	v_cmp_lt_i32_e64 s[22:23], s0, v34
	v_cmp_lt_i32_e64 s[24:25], s24, v34
	v_cmp_lt_i32_e64 s[26:27], s26, v34
	v_cmp_lt_i32_e64 s[28:29], s28, v34
	v_cmp_ge_i32_e64 s[30:31], s30, v34
	v_cndmask_b32_e32 v192, v192, v38, vcc
	v_cndmask_b32_e64 v193, v193, v241, s[6:7]
	v_cndmask_b32_e64 v194, v194, v241, s[8:9]
	v_cndmask_b32_e64 v195, v195, v241, s[10:11]
	v_cndmask_b32_e64 v180, v180, v38, s[12:13]
	v_cndmask_b32_e64 v181, v181, v241, s[16:17]
	v_cndmask_b32_e64 v182, v182, v241, s[18:19]
	v_cndmask_b32_e64 v183, v183, v241, s[20:21]
	v_cndmask_b32_e64 v156, v156, v38, s[22:23]
	v_cndmask_b32_e64 v157, v157, v241, s[24:25]
	v_cndmask_b32_e64 v158, v158, v241, s[26:27]
	v_cndmask_b32_e64 v159, v159, v241, s[28:29]
	v_cndmask_b32_e64 v199, v241, v199, s[30:31]
	v_cndmask_b32_e32 v188, v188, v38, vcc
	v_cndmask_b32_e64 v189, v189, v241, s[6:7]
	v_cndmask_b32_e64 v190, v190, v241, s[8:9]
	v_cndmask_b32_e64 v191, v191, v241, s[10:11]
	v_cndmask_b32_e64 v184, v184, v38, s[12:13]
	v_cndmask_b32_e64 v185, v185, v241, s[16:17]
	v_cndmask_b32_e64 v186, v186, v241, s[18:19]
	v_cndmask_b32_e64 v187, v187, v241, s[20:21]
	v_cndmask_b32_e64 v172, v172, v38, s[22:23]
	v_cndmask_b32_e64 v173, v173, v241, s[24:25]
	v_cndmask_b32_e64 v174, v174, v241, s[26:27]
	v_cndmask_b32_e64 v175, v175, v241, s[28:29]
